# v42 with w_in conversion split 0/2/3/3 per batch (batch 0 goes straight from the adaLN GEMV to its rmsnorm rows)
# speedup vs baseline: 1.0073x; 1.0073x over previous
.LBB0_34:
	s_cmp_lg_u32 s100, 0
	s_cbranch_scc1 .Lp0_go
	s_lshr_b32 s0, s83, 6
	s_and_b32 s1, s83, 63
	s_movk_i32 s4, 0
	s_movk_i32 s5, 0
	s_cmp_eq_u32 s0, 1
	s_cselect_b32 s4, 2, s4
	s_cselect_b32 s5, 0, s5
	s_cmp_eq_u32 s0, 2
	s_cselect_b32 s4, 3, s4
	s_cselect_b32 s5, 128, s5
	s_cmp_eq_u32 s0, 3
	s_cselect_b32 s4, 3, s4
	s_cselect_b32 s5, 320, s5
	s_mul_i32 s6, s1, s4
	s_add_i32 s8, s5, s6
	s_add_i32 s10, s8, s4
